# peel1 kernel plus grid barrier release: workgroups that are not the last arriver of their XCD poll the top-level generation word directly instead of the per-XCD generation word (one release hop less),
# speedup vs baseline: 1.0123x; 1.0123x over previous
; __device__ __forceinline__ unsigned xb_ld(unsigned* p)              { return __hip_atomic_load(p, __ATOMIC_RELAXED, __HIP_MEMORY_SCOPE_AGENT); }
; __device__ __forceinline__ unsigned xb_add(unsigned* p, unsigned v) { return __hip_atomic_fetch_add(p, v, __ATOMIC_RELAXED, __HIP_MEMORY_SCOPE_AGENT); }
; #define XB_SPIN(cond, bar) do { unsigned _sp = 0; while (cond) { __builtin_amdgcn_s_sleep(1); \
;     if ((++_sp & 255u) == 0u) { if (xb_ld(&(bar)[XB_TMO])) break; if (_sp > XB_SPIN_CAP) { atomicAdd(&(bar)[XB_TMO], 1u); break; } } } } while (0)
; __device__ __forceinline__ void xcd_barrier(const XcdBarrier& b) {
;     ...
;         const unsigned old = xb_add(&bar[XB_XSUB(b.x)], 1u);
;         const unsigned gen = old / nloc;
;         if (old + 1u == (gen + 1u) * nloc) {
;             __builtin_amdgcn_fence(__ATOMIC_RELEASE, "agent");
;             asm volatile("s_waitcnt vmcnt(0)" ::: "memory");
;             const unsigned og = xb_add(&bar[XB_TOP], 1u);
;             const unsigned tg = og / nx;
;             if (og + 1u == (tg + 1u) * nx) xb_add(&bar[XB_TOPGEN], 1u);
;             else XB_SPIN(xb_ld(&bar[XB_TOPGEN]) == tg, bar);
;             __builtin_amdgcn_fence(__ATOMIC_ACQUIRE, "agent");
;             xb_add(&bar[XB_XGEN(b.x)], 1u);
;             asm volatile("s_waitcnt vmcnt(0)" ::: "memory");
;         } else {
;             XB_SPIN(xb_ld(&bar[XB_XGEN(b.x)]) == gen, bar);
;             __builtin_amdgcn_fence(__ATOMIC_ACQUIRE, "agent");
;             asm volatile("s_waitcnt vmcnt(0)" ::: "memory");
.LBB0_222:
	s_or_b64 exec, exec, s[6:7]
	v_cvt_f32_u32_e32 v4, v2
	s_waitcnt vmcnt(0)
	v_readfirstlane_b32 s6, v3
	v_sub_u32_e32 v3, 0, v2
	v_rcp_iflag_f32_e32 v4, v4
	v_add_u32_e32 v5, s6, v1
	v_mul_f32_e32 v4, 0x4f7ffffe, v4
	v_cvt_u32_f32_e32 v4, v4
	v_mul_lo_u32 v1, v3, v4
	v_mul_hi_u32 v1, v4, v1
	v_add_u32_e32 v1, v4, v1
	v_mul_hi_u32 v1, v5, v1
	v_mul_lo_u32 v3, v1, v2
	v_sub_u32_e32 v3, v5, v3
	v_add_u32_e32 v4, 1, v1
	v_cmp_ge_u32_e32 vcc, v3, v2
	s_nop 1
	v_cndmask_b32_e32 v1, v1, v4, vcc
	v_sub_u32_e32 v4, v3, v2
	v_cndmask_b32_e32 v3, v3, v4, vcc
	v_add_u32_e32 v4, 1, v1
	v_cmp_ge_u32_e32 vcc, v3, v2
	v_add_u32_e32 v3, 1, v5
	s_nop 0
	v_cndmask_b32_e32 v1, v1, v4, vcc
	v_mul_lo_u32 v4, v2, v1
	v_add_u32_e32 v2, v4, v2
	v_cmp_ne_u32_e32 vcc, v3, v2
	s_and_saveexec_b64 s[6:7], vcc
	s_xor_b64 s[6:7], exec, s[6:7]
	s_cbranch_execz .LBB0_236
	v_readlane_b32 s10, v249, 25
	v_readlane_b32 s11, v249, 26
	s_waitcnt lgkmcnt(0)
	s_nop 3
	global_load_dword v0, v80, s[10:11] sc1
	s_waitcnt vmcnt(0)
	v_cmp_eq_u32_e32 vcc, v0, v1
	s_and_saveexec_b64 s[10:11], vcc
	s_cbranch_execz .LBB0_235
	s_mov_b32 s20, 1
	s_mov_b64 s[12:13], 0
	s_branch .LBB0_226

; __device__ __forceinline__ unsigned xb_ld(unsigned* p)              { return __hip_atomic_load(p, __ATOMIC_RELAXED, __HIP_MEMORY_SCOPE_AGENT); }
; #define XB_SPIN(cond, bar) do { unsigned _sp = 0; while (cond) { __builtin_amdgcn_s_sleep(1); \
;     if ((++_sp & 255u) == 0u) { if (xb_ld(&(bar)[XB_TMO])) break; if (_sp > XB_SPIN_CAP) { atomicAdd(&(bar)[XB_TMO], 1u); break; } } } } while (0)
; __device__ __forceinline__ void xcd_barrier(const XcdBarrier& b) {
;     ...
;             XB_SPIN(xb_ld(&bar[XB_XGEN(b.x)]) == gen, bar);
.LBB0_230:
	v_readlane_b32 s16, v249, 25
	v_readlane_b32 s17, v249, 26
	s_add_i32 s20, s20, 1
	s_mov_b64 s[18:19], -1
	s_nop 2
	global_load_dword v0, v80, s[16:17] sc1
	s_waitcnt vmcnt(0)
	v_cmp_ne_u32_e32 vcc, v0, v1
	s_orn2_b64 s[16:17], vcc, exec
	s_branch .LBB0_225

; __device__ __forceinline__ unsigned xb_ld(unsigned* p)              { return __hip_atomic_load(p, __ATOMIC_RELAXED, __HIP_MEMORY_SCOPE_AGENT); }
; __device__ __forceinline__ unsigned xb_add(unsigned* p, unsigned v) { return __hip_atomic_fetch_add(p, v, __ATOMIC_RELAXED, __HIP_MEMORY_SCOPE_AGENT); }
; #define XB_SPIN(cond, bar) do { unsigned _sp = 0; while (cond) { __builtin_amdgcn_s_sleep(1); \
;     if ((++_sp & 255u) == 0u) { if (xb_ld(&(bar)[XB_TMO])) break; if (_sp > XB_SPIN_CAP) { atomicAdd(&(bar)[XB_TMO], 1u); break; } } } } while (0)
; __device__ __forceinline__ void xcd_barrier(const XcdBarrier& b) {
;     ...
;         const unsigned old = xb_add(&bar[XB_XSUB(b.x)], 1u);
;         const unsigned gen = old / nloc;
;         if (old + 1u == (gen + 1u) * nloc) {
;             __builtin_amdgcn_fence(__ATOMIC_RELEASE, "agent");
;             asm volatile("s_waitcnt vmcnt(0)" ::: "memory");
;             const unsigned og = xb_add(&bar[XB_TOP], 1u);
;             const unsigned tg = og / nx;
;             if (og + 1u == (tg + 1u) * nx) xb_add(&bar[XB_TOPGEN], 1u);
;             else XB_SPIN(xb_ld(&bar[XB_TOPGEN]) == tg, bar);
;             __builtin_amdgcn_fence(__ATOMIC_ACQUIRE, "agent");
;             xb_add(&bar[XB_XGEN(b.x)], 1u);
;             asm volatile("s_waitcnt vmcnt(0)" ::: "memory");
;         } else {
;             XB_SPIN(xb_ld(&bar[XB_XGEN(b.x)]) == gen, bar);
;             __builtin_amdgcn_fence(__ATOMIC_ACQUIRE, "agent");
;             asm volatile("s_waitcnt vmcnt(0)" ::: "memory");
.LBB0_324:
	s_or_b64 exec, exec, s[6:7]
	v_cvt_f32_u32_e32 v4, v2
	s_waitcnt vmcnt(0)
	v_readfirstlane_b32 s6, v3
	v_sub_u32_e32 v3, 0, v2
	v_rcp_iflag_f32_e32 v4, v4
	v_add_u32_e32 v5, s6, v1
	v_mul_f32_e32 v4, 0x4f7ffffe, v4
	v_cvt_u32_f32_e32 v4, v4
	v_mul_lo_u32 v1, v3, v4
	v_mul_hi_u32 v1, v4, v1
	v_add_u32_e32 v1, v4, v1
	v_mul_hi_u32 v1, v5, v1
	v_mul_lo_u32 v3, v1, v2
	v_sub_u32_e32 v3, v5, v3
	v_add_u32_e32 v4, 1, v1
	v_cmp_ge_u32_e32 vcc, v3, v2
	s_nop 1
	v_cndmask_b32_e32 v1, v1, v4, vcc
	v_sub_u32_e32 v4, v3, v2
	v_cndmask_b32_e32 v3, v3, v4, vcc
	v_add_u32_e32 v4, 1, v1
	v_cmp_ge_u32_e32 vcc, v3, v2
	v_add_u32_e32 v3, 1, v5
	s_nop 0
	v_cndmask_b32_e32 v1, v1, v4, vcc
	v_mul_lo_u32 v4, v2, v1
	v_add_u32_e32 v2, v4, v2
	v_cmp_ne_u32_e32 vcc, v3, v2
	s_and_saveexec_b64 s[6:7], vcc
	s_xor_b64 s[6:7], exec, s[6:7]
	s_cbranch_execz .LBB0_338
	v_readlane_b32 s8, v249, 25
	v_readlane_b32 s9, v249, 26
	s_waitcnt lgkmcnt(0)
	s_nop 3
	global_load_dword v0, v80, s[8:9] sc1
	s_waitcnt vmcnt(0)
	v_cmp_eq_u32_e32 vcc, v0, v1
	s_and_saveexec_b64 s[8:9], vcc
	s_cbranch_execz .LBB0_337
	s_mov_b32 s20, 1
	s_mov_b64 s[10:11], 0
	s_branch .LBB0_328

; __device__ __forceinline__ unsigned xb_ld(unsigned* p)              { return __hip_atomic_load(p, __ATOMIC_RELAXED, __HIP_MEMORY_SCOPE_AGENT); }
; #define XB_SPIN(cond, bar) do { unsigned _sp = 0; while (cond) { __builtin_amdgcn_s_sleep(1); \
;     if ((++_sp & 255u) == 0u) { if (xb_ld(&(bar)[XB_TMO])) break; if (_sp > XB_SPIN_CAP) { atomicAdd(&(bar)[XB_TMO], 1u); break; } } } } while (0)
; __device__ __forceinline__ void xcd_barrier(const XcdBarrier& b) {
;     ...
;             XB_SPIN(xb_ld(&bar[XB_XGEN(b.x)]) == gen, bar);
.LBB0_332:
	v_readlane_b32 s14, v249, 25
	v_readlane_b32 s15, v249, 26
	s_add_i32 s20, s20, 1
	s_mov_b64 s[16:17], -1
	s_nop 2
	global_load_dword v0, v80, s[14:15] sc1
	s_waitcnt vmcnt(0)
	v_cmp_ne_u32_e32 vcc, v0, v1
	s_orn2_b64 s[14:15], vcc, exec
	s_branch .LBB0_327
